# saddr-form LDS-DMA addressing also in the DN/OUT and WIN GEMM K-loops (no 64-bit VALU address adds in the load segments)
# baseline (speedup 1.0000x reference)
.LBB0_403:
	s_add_u32 s66, s64, 0xfffc0080
	s_addc_u32 s67, s65, -1
	s_add_i32 s75, 0, 0x10000
	s_cmp_eq_u32 s74, 12
	s_cselect_b32 s69, s59, s67
	s_cselect_b32 s68, s70, s66
	v_add_u32_e32 v0, s75, v169
	s_cselect_b32 s67, s57, s73
	s_cselect_b32 s66, s71, s72
	s_add_i32 s79, 0, 0x14000
	ds_read_b128 v[134:137], v0
	ds_read_b128 v[138:141], v0 offset:1024
	ds_read_b128 v[142:145], v0 offset:2048
	ds_read_b128 v[146:149], v0 offset:3072
	v_add_u32_e32 v0, s79, v169
	ds_read_b128 v[150:153], v0
	ds_read_b128 v[154:157], v0 offset:1024
	ds_read_b128 v[158:161], v0 offset:2048
	ds_read_b128 v[162:165], v0 offset:3072
	s_add_i32 m0, s9, 0xc000
	ds_read_b128 v[182:185], v171
	ds_read_b128 v[186:189], v171 offset:1024
	ds_read_b128 v[190:193], v171 offset:2048
	ds_read_b128 v[194:197], v171 offset:3072
	ds_read_b128 v[208:211], v171 offset:4096
	ds_read_b128 v[212:215], v171 offset:5120
	ds_read_b128 v[216:219], v171 offset:6144
	ds_read_b128 v[232:235], v171 offset:7168
	global_load_lds_dwordx4 v180, s[64:65]
	s_add_i32 m0, s9, 0xe000
	s_nop 0
	global_load_lds_dwordx4 v178, s[64:65]
	s_waitcnt vmcnt(8)
	s_waitcnt lgkmcnt(0)
	s_barrier
	s_setprio 1
	s_waitcnt lgkmcnt(0)
	v_mfma_f32_16x16x32_bf16 v[130:133], v[134:137], v[182:185], v[130:133]
	v_mfma_f32_16x16x32_bf16 v[126:129], v[142:145], v[182:185], v[126:129]
	v_mfma_f32_16x16x32_bf16 v[122:125], v[134:137], v[190:193], v[122:125]
	v_mfma_f32_16x16x32_bf16 v[118:121], v[142:145], v[190:193], v[118:121]
	v_mfma_f32_16x16x32_bf16 v[114:117], v[134:137], v[208:211], v[114:117]
	v_mfma_f32_16x16x32_bf16 v[110:113], v[142:145], v[208:211], v[110:113]
	v_mfma_f32_16x16x32_bf16 v[106:109], v[134:137], v[216:219], v[106:109]
	v_mfma_f32_16x16x32_bf16 v[102:105], v[142:145], v[216:219], v[102:105]
	v_mfma_f32_16x16x32_bf16 v[130:133], v[138:141], v[186:189], v[130:133]
	v_mfma_f32_16x16x32_bf16 v[126:129], v[146:149], v[186:189], v[126:129]
	v_mfma_f32_16x16x32_bf16 v[122:125], v[138:141], v[194:197], v[122:125]
	v_mfma_f32_16x16x32_bf16 v[118:121], v[146:149], v[194:197], v[118:121]
	v_mfma_f32_16x16x32_bf16 v[114:117], v[138:141], v[212:215], v[114:117]
	v_mfma_f32_16x16x32_bf16 v[110:113], v[146:149], v[212:215], v[110:113]
	v_mfma_f32_16x16x32_bf16 v[106:109], v[138:141], v[232:235], v[106:109]
	v_mfma_f32_16x16x32_bf16 v[102:105], v[146:149], v[232:235], v[102:105]
	s_setprio 0
	s_setprio 1
	v_mfma_f32_16x16x32_bf16 v[62:65], v[150:153], v[182:185], v[62:65]
	v_mfma_f32_16x16x32_bf16 v[58:61], v[158:161], v[182:185], v[58:61]
	v_mfma_f32_16x16x32_bf16 v[54:57], v[150:153], v[190:193], v[54:57]
	v_mfma_f32_16x16x32_bf16 v[50:53], v[158:161], v[190:193], v[50:53]
	v_mfma_f32_16x16x32_bf16 v[46:49], v[150:153], v[208:211], v[46:49]
	v_mfma_f32_16x16x32_bf16 v[42:45], v[158:161], v[208:211], v[42:45]
	v_mfma_f32_16x16x32_bf16 v[38:41], v[150:153], v[216:219], v[38:41]
	v_mfma_f32_16x16x32_bf16 v[34:37], v[158:161], v[216:219], v[34:37]
	v_mfma_f32_16x16x32_bf16 v[62:65], v[154:157], v[186:189], v[62:65]
	v_mfma_f32_16x16x32_bf16 v[58:61], v[162:165], v[186:189], v[58:61]
	v_mfma_f32_16x16x32_bf16 v[54:57], v[154:157], v[194:197], v[54:57]
	v_mfma_f32_16x16x32_bf16 v[50:53], v[162:165], v[194:197], v[50:53]
	v_mfma_f32_16x16x32_bf16 v[46:49], v[154:157], v[212:215], v[46:49]
	v_mfma_f32_16x16x32_bf16 v[42:45], v[162:165], v[212:215], v[42:45]
	v_mfma_f32_16x16x32_bf16 v[38:41], v[154:157], v[232:235], v[38:41]
	v_mfma_f32_16x16x32_bf16 v[34:37], v[162:165], v[232:235], v[34:37]
	s_setprio 0
	s_barrier
	s_add_i32 s75, s75, s8
	s_mov_b32 m0, s75
	ds_read_b128 v[182:185], v171 offset:16384
	ds_read_b128 v[186:189], v171 offset:17408
	ds_read_b128 v[190:193], v171 offset:18432
	ds_read_b128 v[194:197], v171 offset:19456
	ds_read_b128 v[208:211], v171 offset:20480
	ds_read_b128 v[212:215], v171 offset:21504
	ds_read_b128 v[216:219], v171 offset:22528
	ds_read_b128 v[232:235], v171 offset:23552
	global_load_lds_dwordx4 v166, s[66:67]
	s_add_i32 m0, s75, 0x2000
	s_add_u32 s76, s66, 0x40000
	s_addc_u32 s77, s67, 0
	s_add_i32 s75, s79, s8
	global_load_lds_dwordx4 v94, s[66:67]
	s_mov_b32 m0, s75
	s_nop 0
	global_load_lds_dwordx4 v166, s[76:77]
	s_add_i32 m0, s75, 0x2000
	s_nop 0
	global_load_lds_dwordx4 v94, s[76:77]
	s_mov_b32 m0, s9
	s_nop 0
	global_load_lds_dwordx4 v166, s[68:69]
	s_mov_b32 m0, s12
	s_nop 0
	global_load_lds_dwordx4 v94, s[68:69]
	s_waitcnt vmcnt(8)
	s_waitcnt lgkmcnt(0)
	s_barrier
	s_setprio 1
	s_waitcnt lgkmcnt(0)
	v_mfma_f32_16x16x32_bf16 v[98:101], v[134:137], v[182:185], v[98:101]
	v_mfma_f32_16x16x32_bf16 v[90:93], v[142:145], v[182:185], v[90:93]
	v_mfma_f32_16x16x32_bf16 v[86:89], v[134:137], v[190:193], v[86:89]
	v_mfma_f32_16x16x32_bf16 v[82:85], v[142:145], v[190:193], v[82:85]
	v_mfma_f32_16x16x32_bf16 v[78:81], v[134:137], v[208:211], v[78:81]
	v_mfma_f32_16x16x32_bf16 v[74:77], v[142:145], v[208:211], v[74:77]
	v_mfma_f32_16x16x32_bf16 v[70:73], v[134:137], v[216:219], v[70:73]
	v_mfma_f32_16x16x32_bf16 v[66:69], v[142:145], v[216:219], v[66:69]
	v_mfma_f32_16x16x32_bf16 v[98:101], v[138:141], v[186:189], v[98:101]
	v_mfma_f32_16x16x32_bf16 v[90:93], v[146:149], v[186:189], v[90:93]
	v_mfma_f32_16x16x32_bf16 v[86:89], v[138:141], v[194:197], v[86:89]
	v_mfma_f32_16x16x32_bf16 v[82:85], v[146:149], v[194:197], v[82:85]
	v_mfma_f32_16x16x32_bf16 v[78:81], v[138:141], v[212:215], v[78:81]
	v_mfma_f32_16x16x32_bf16 v[74:77], v[146:149], v[212:215], v[74:77]
	v_mfma_f32_16x16x32_bf16 v[70:73], v[138:141], v[232:235], v[70:73]
	v_mfma_f32_16x16x32_bf16 v[66:69], v[146:149], v[232:235], v[66:69]
	s_setprio 0
	s_setprio 1
	v_mfma_f32_16x16x32_bf16 v[30:33], v[150:153], v[182:185], v[30:33]
	v_mfma_f32_16x16x32_bf16 v[26:29], v[158:161], v[182:185], v[26:29]
	v_mfma_f32_16x16x32_bf16 v[22:25], v[150:153], v[190:193], v[22:25]
	v_mfma_f32_16x16x32_bf16 v[18:21], v[158:161], v[190:193], v[18:21]
	v_mfma_f32_16x16x32_bf16 v[14:17], v[150:153], v[208:211], v[14:17]
	v_mfma_f32_16x16x32_bf16 v[10:13], v[158:161], v[208:211], v[10:13]
	v_mfma_f32_16x16x32_bf16 v[6:9], v[150:153], v[216:219], v[6:9]
	v_mfma_f32_16x16x32_bf16 v[2:5], v[158:161], v[216:219], v[2:5]
	v_mfma_f32_16x16x32_bf16 v[30:33], v[154:157], v[186:189], v[30:33]
	v_mfma_f32_16x16x32_bf16 v[26:29], v[162:165], v[186:189], v[26:29]
	v_mfma_f32_16x16x32_bf16 v[22:25], v[154:157], v[194:197], v[22:25]
	v_mfma_f32_16x16x32_bf16 v[18:21], v[162:165], v[194:197], v[18:21]
	v_mfma_f32_16x16x32_bf16 v[14:17], v[154:157], v[212:215], v[14:17]
	v_mfma_f32_16x16x32_bf16 v[10:13], v[162:165], v[212:215], v[10:13]
	v_mfma_f32_16x16x32_bf16 v[6:9], v[154:157], v[232:235], v[6:9]
	v_mfma_f32_16x16x32_bf16 v[2:5], v[162:165], v[232:235], v[2:5]
	s_setprio 0
	s_barrier
	s_add_i32 s75, 0, 0x18000
	v_add_u32_e32 v0, s75, v169
	s_add_i32 s76, 0, 0x1c000
	ds_read_b128 v[134:137], v0
	ds_read_b128 v[138:141], v0 offset:1024
	ds_read_b128 v[142:145], v0 offset:2048
	ds_read_b128 v[146:149], v0 offset:3072
	v_add_u32_e32 v0, s76, v169
	ds_read_b128 v[150:153], v0
	ds_read_b128 v[154:157], v0 offset:1024
	ds_read_b128 v[158:161], v0 offset:2048
	ds_read_b128 v[162:165], v0 offset:3072
	s_add_u32 s68, s68, 0x40000
	s_addc_u32 s69, s69, 0
	s_mov_b32 m0, s13
	ds_read_b128 v[182:185], v171 offset:32768
	ds_read_b128 v[186:189], v171 offset:33792
	ds_read_b128 v[190:193], v171 offset:34816
	ds_read_b128 v[194:197], v171 offset:35840
	ds_read_b128 v[208:211], v171 offset:36864
	ds_read_b128 v[212:215], v171 offset:37888
	ds_read_b128 v[216:219], v171 offset:38912
	ds_read_b128 v[232:235], v171 offset:39936
	global_load_lds_dwordx4 v166, s[68:69]
	s_mov_b32 m0, s25
	s_nop 0
	global_load_lds_dwordx4 v94, s[68:69]
	s_waitcnt vmcnt(8)
	s_waitcnt lgkmcnt(0)
	s_barrier
	s_setprio 1
	s_waitcnt lgkmcnt(0)
	v_mfma_f32_16x16x32_bf16 v[130:133], v[134:137], v[182:185], v[130:133]
	v_mfma_f32_16x16x32_bf16 v[126:129], v[142:145], v[182:185], v[126:129]
	v_mfma_f32_16x16x32_bf16 v[122:125], v[134:137], v[190:193], v[122:125]
	v_mfma_f32_16x16x32_bf16 v[118:121], v[142:145], v[190:193], v[118:121]
	v_mfma_f32_16x16x32_bf16 v[114:117], v[134:137], v[208:211], v[114:117]
	v_mfma_f32_16x16x32_bf16 v[110:113], v[142:145], v[208:211], v[110:113]
	v_mfma_f32_16x16x32_bf16 v[106:109], v[134:137], v[216:219], v[106:109]
	v_mfma_f32_16x16x32_bf16 v[102:105], v[142:145], v[216:219], v[102:105]
	v_mfma_f32_16x16x32_bf16 v[130:133], v[138:141], v[186:189], v[130:133]
	v_mfma_f32_16x16x32_bf16 v[126:129], v[146:149], v[186:189], v[126:129]
	v_mfma_f32_16x16x32_bf16 v[122:125], v[138:141], v[194:197], v[122:125]
	v_mfma_f32_16x16x32_bf16 v[118:121], v[146:149], v[194:197], v[118:121]
	v_mfma_f32_16x16x32_bf16 v[114:117], v[138:141], v[212:215], v[114:117]
	v_mfma_f32_16x16x32_bf16 v[110:113], v[146:149], v[212:215], v[110:113]
	v_mfma_f32_16x16x32_bf16 v[106:109], v[138:141], v[232:235], v[106:109]
	v_mfma_f32_16x16x32_bf16 v[102:105], v[146:149], v[232:235], v[102:105]
	s_setprio 0
	s_setprio 1
	v_mfma_f32_16x16x32_bf16 v[62:65], v[150:153], v[182:185], v[62:65]
	v_mfma_f32_16x16x32_bf16 v[58:61], v[158:161], v[182:185], v[58:61]
	v_mfma_f32_16x16x32_bf16 v[54:57], v[150:153], v[190:193], v[54:57]
	v_mfma_f32_16x16x32_bf16 v[50:53], v[158:161], v[190:193], v[50:53]
	v_mfma_f32_16x16x32_bf16 v[46:49], v[150:153], v[208:211], v[46:49]
	v_mfma_f32_16x16x32_bf16 v[42:45], v[158:161], v[208:211], v[42:45]
	v_mfma_f32_16x16x32_bf16 v[38:41], v[150:153], v[216:219], v[38:41]
	v_mfma_f32_16x16x32_bf16 v[34:37], v[158:161], v[216:219], v[34:37]
	v_mfma_f32_16x16x32_bf16 v[62:65], v[154:157], v[186:189], v[62:65]
	v_mfma_f32_16x16x32_bf16 v[58:61], v[162:165], v[186:189], v[58:61]
	v_mfma_f32_16x16x32_bf16 v[54:57], v[154:157], v[194:197], v[54:57]
	v_mfma_f32_16x16x32_bf16 v[50:53], v[162:165], v[194:197], v[50:53]
	v_mfma_f32_16x16x32_bf16 v[46:49], v[154:157], v[212:215], v[46:49]
	v_mfma_f32_16x16x32_bf16 v[42:45], v[162:165], v[212:215], v[42:45]
	v_mfma_f32_16x16x32_bf16 v[38:41], v[154:157], v[232:235], v[38:41]
	v_mfma_f32_16x16x32_bf16 v[34:37], v[162:165], v[232:235], v[34:37]
	s_setprio 0
	s_barrier
	s_add_i32 s79, s75, s8
	s_add_i32 m0, s79, 0xffffff80
	ds_read_b128 v[182:185], v171 offset:49152
	ds_read_b128 v[186:189], v171 offset:50176
	ds_read_b128 v[190:193], v171 offset:51200
	ds_read_b128 v[194:197], v171 offset:52224
	ds_read_b128 v[208:211], v171 offset:53248
	ds_read_b128 v[212:215], v171 offset:54272
	ds_read_b128 v[216:219], v171 offset:55296
	ds_read_b128 v[232:235], v171 offset:56320
	global_load_lds_dwordx4 v166, s[66:67] offset:128
	s_add_i32 m0, s79, 0x1f80
	s_nop 0
	global_load_lds_dwordx4 v94, s[66:67] offset:128
	s_add_i32 s79, s76, s8
	s_add_u32 s66, s66, 0x40080
	s_addc_u32 s67, s67, 0
	s_mov_b32 m0, s79
	s_nop 0
	global_load_lds_dwordx4 v166, s[66:67]
	s_add_i32 m0, s79, 0x2000
	s_nop 0
	global_load_lds_dwordx4 v94, s[66:67]
	s_add_u32 s68, s68, 0xfffc0080
	s_addc_u32 s69, s69, -1
	s_mov_b32 m0, s33
	s_nop 0
	global_load_lds_dwordx4 v166, s[68:69]
	s_mov_b32 m0, s80
	s_nop 0
	global_load_lds_dwordx4 v94, s[68:69]
	s_waitcnt vmcnt(8)
	s_waitcnt lgkmcnt(0)
	s_barrier
	s_setprio 1
	s_waitcnt lgkmcnt(0)
	v_mfma_f32_16x16x32_bf16 v[98:101], v[134:137], v[182:185], v[98:101]
	v_mfma_f32_16x16x32_bf16 v[90:93], v[142:145], v[182:185], v[90:93]
	v_mfma_f32_16x16x32_bf16 v[86:89], v[134:137], v[190:193], v[86:89]
	v_mfma_f32_16x16x32_bf16 v[82:85], v[142:145], v[190:193], v[82:85]
	v_mfma_f32_16x16x32_bf16 v[78:81], v[134:137], v[208:211], v[78:81]
	v_mfma_f32_16x16x32_bf16 v[74:77], v[142:145], v[208:211], v[74:77]
	v_mfma_f32_16x16x32_bf16 v[70:73], v[134:137], v[216:219], v[70:73]
	v_mfma_f32_16x16x32_bf16 v[66:69], v[142:145], v[216:219], v[66:69]
	v_mfma_f32_16x16x32_bf16 v[98:101], v[138:141], v[186:189], v[98:101]
	v_mfma_f32_16x16x32_bf16 v[90:93], v[146:149], v[186:189], v[90:93]
	v_mfma_f32_16x16x32_bf16 v[86:89], v[138:141], v[194:197], v[86:89]
	v_mfma_f32_16x16x32_bf16 v[82:85], v[146:149], v[194:197], v[82:85]
	v_mfma_f32_16x16x32_bf16 v[78:81], v[138:141], v[212:215], v[78:81]
	v_mfma_f32_16x16x32_bf16 v[74:77], v[146:149], v[212:215], v[74:77]
	v_mfma_f32_16x16x32_bf16 v[70:73], v[138:141], v[232:235], v[70:73]
	v_mfma_f32_16x16x32_bf16 v[66:69], v[146:149], v[232:235], v[66:69]
	s_setprio 0
	s_setprio 1
	v_mfma_f32_16x16x32_bf16 v[30:33], v[150:153], v[182:185], v[30:33]
	v_mfma_f32_16x16x32_bf16 v[26:29], v[158:161], v[182:185], v[26:29]
	v_mfma_f32_16x16x32_bf16 v[22:25], v[150:153], v[190:193], v[22:25]
	v_mfma_f32_16x16x32_bf16 v[18:21], v[158:161], v[190:193], v[18:21]
	v_mfma_f32_16x16x32_bf16 v[14:17], v[150:153], v[208:211], v[14:17]
	v_mfma_f32_16x16x32_bf16 v[10:13], v[158:161], v[208:211], v[10:13]
	v_mfma_f32_16x16x32_bf16 v[6:9], v[150:153], v[216:219], v[6:9]
	v_mfma_f32_16x16x32_bf16 v[2:5], v[158:161], v[216:219], v[2:5]
	v_mfma_f32_16x16x32_bf16 v[30:33], v[154:157], v[186:189], v[30:33]
	v_mfma_f32_16x16x32_bf16 v[26:29], v[162:165], v[186:189], v[26:29]
	v_mfma_f32_16x16x32_bf16 v[22:25], v[154:157], v[194:197], v[22:25]
	v_mfma_f32_16x16x32_bf16 v[18:21], v[162:165], v[194:197], v[18:21]
	v_mfma_f32_16x16x32_bf16 v[14:17], v[154:157], v[212:215], v[14:17]
	v_mfma_f32_16x16x32_bf16 v[10:13], v[162:165], v[212:215], v[10:13]
	v_mfma_f32_16x16x32_bf16 v[6:9], v[154:157], v[232:235], v[6:9]
	v_mfma_f32_16x16x32_bf16 v[2:5], v[162:165], v[232:235], v[2:5]
	s_setprio 0
	s_barrier
	s_add_i32 s74, s74, 2
	s_add_u32 s72, s72, 0x100
	s_addc_u32 s73, s73, 0
	s_add_u32 s64, s64, 0x100
	s_addc_u32 s65, s65, 0
	s_cmp_gt_u32 s74, 13
	s_cbranch_scc0 .LBB0_403
	s_and_b64 vcc, exec, s[30:31]
	s_cbranch_vccz .LBB0_406
	s_barrier

.LBB0_528:
	s_add_i32 s53, s30, 2
	s_add_u32 s54, s22, 0x80
	s_addc_u32 s31, s23, 0
	s_add_i32 s56, 0, 0x10000
	s_cmp_eq_u32 s46, s30
	s_cselect_b32 s31, s1, s31
	s_cselect_b32 s30, s0, s54
	s_cselect_b32 s55, s21, s52
	s_cselect_b32 s54, s20, s51
	s_add_i32 s57, 0, 0x14000
	v_add_u32_e32 v152, s56, v232
	v_add_u32_e32 v168, s57, v232
	ds_read_b128 v[140:143], v152
	ds_read_b128 v[144:147], v152 offset:1024
	ds_read_b128 v[148:151], v152 offset:2048
	ds_read_b128 v[152:155], v152 offset:3072
	ds_read_b128 v[156:159], v168
	ds_read_b128 v[160:163], v168 offset:1024
	ds_read_b128 v[164:167], v168 offset:2048
	ds_read_b128 v[168:171], v168 offset:3072
	s_add_i32 m0, s28, 0xc000
	ds_read_b128 v[172:175], v236
	ds_read_b128 v[176:179], v236 offset:1024
	ds_read_b128 v[180:183], v236 offset:2048
	ds_read_b128 v[184:187], v236 offset:3072
	ds_read_b128 v[188:191], v236 offset:4096
	ds_read_b128 v[192:195], v236 offset:5120
	ds_read_b128 v[208:211], v236 offset:6144
	ds_read_b128 v[212:215], v236 offset:7168
	global_load_lds_dwordx4 v138, s[22:23]
	s_add_i32 m0, s28, 0xe000
	s_nop 0
	global_load_lds_dwordx4 v136, s[22:23]
	s_waitcnt vmcnt(8)
	s_waitcnt lgkmcnt(0)
	s_barrier
	s_setprio 1
	s_waitcnt lgkmcnt(0)
	v_mfma_f32_16x16x32_bf16 v[130:133], v[140:143], v[172:175], v[130:133]
	v_mfma_f32_16x16x32_bf16 v[126:129], v[148:151], v[172:175], v[126:129]
	v_mfma_f32_16x16x32_bf16 v[114:117], v[140:143], v[180:183], v[114:117]
	v_mfma_f32_16x16x32_bf16 v[110:113], v[148:151], v[180:183], v[110:113]
	v_mfma_f32_16x16x32_bf16 v[98:101], v[140:143], v[188:191], v[98:101]
	v_mfma_f32_16x16x32_bf16 v[90:93], v[148:151], v[188:191], v[90:93]
	v_mfma_f32_16x16x32_bf16 v[78:81], v[140:143], v[208:211], v[78:81]
	v_mfma_f32_16x16x32_bf16 v[74:77], v[148:151], v[208:211], v[74:77]
	v_mfma_f32_16x16x32_bf16 v[130:133], v[144:147], v[176:179], v[130:133]
	v_mfma_f32_16x16x32_bf16 v[126:129], v[152:155], v[176:179], v[126:129]
	v_mfma_f32_16x16x32_bf16 v[114:117], v[144:147], v[184:187], v[114:117]
	v_mfma_f32_16x16x32_bf16 v[110:113], v[152:155], v[184:187], v[110:113]
	v_mfma_f32_16x16x32_bf16 v[98:101], v[144:147], v[192:195], v[98:101]
	v_mfma_f32_16x16x32_bf16 v[90:93], v[152:155], v[192:195], v[90:93]
	v_mfma_f32_16x16x32_bf16 v[78:81], v[144:147], v[212:215], v[78:81]
	v_mfma_f32_16x16x32_bf16 v[74:77], v[152:155], v[212:215], v[74:77]
	s_setprio 0
	s_setprio 1
	v_mfma_f32_16x16x32_bf16 v[122:125], v[156:159], v[172:175], v[122:125]
	v_mfma_f32_16x16x32_bf16 v[118:121], v[164:167], v[172:175], v[118:121]
	v_mfma_f32_16x16x32_bf16 v[106:109], v[156:159], v[180:183], v[106:109]
	v_mfma_f32_16x16x32_bf16 v[102:105], v[164:167], v[180:183], v[102:105]
	v_mfma_f32_16x16x32_bf16 v[86:89], v[156:159], v[188:191], v[86:89]
	v_mfma_f32_16x16x32_bf16 v[82:85], v[164:167], v[188:191], v[82:85]
	v_mfma_f32_16x16x32_bf16 v[70:73], v[156:159], v[208:211], v[70:73]
	v_mfma_f32_16x16x32_bf16 v[66:69], v[164:167], v[208:211], v[66:69]
	v_mfma_f32_16x16x32_bf16 v[122:125], v[160:163], v[176:179], v[122:125]
	v_mfma_f32_16x16x32_bf16 v[118:121], v[168:171], v[176:179], v[118:121]
	v_mfma_f32_16x16x32_bf16 v[106:109], v[160:163], v[184:187], v[106:109]
	v_mfma_f32_16x16x32_bf16 v[102:105], v[168:171], v[184:187], v[102:105]
	v_mfma_f32_16x16x32_bf16 v[86:89], v[160:163], v[192:195], v[86:89]
	v_mfma_f32_16x16x32_bf16 v[82:85], v[168:171], v[192:195], v[82:85]
	v_mfma_f32_16x16x32_bf16 v[70:73], v[160:163], v[212:215], v[70:73]
	v_mfma_f32_16x16x32_bf16 v[66:69], v[168:171], v[212:215], v[66:69]
	s_setprio 0
	s_barrier
	s_add_i32 s56, s56, s25
	s_mov_b32 m0, s56
	ds_read_b128 v[172:175], v236 offset:16384
	ds_read_b128 v[176:179], v236 offset:17408
	ds_read_b128 v[180:183], v236 offset:18432
	ds_read_b128 v[184:187], v236 offset:19456
	ds_read_b128 v[188:191], v236 offset:20480
	ds_read_b128 v[192:195], v236 offset:21504
	ds_read_b128 v[208:211], v236 offset:22528
	ds_read_b128 v[212:215], v236 offset:23552
	global_load_lds_dwordx4 v0, s[54:55]
	s_add_i32 m0, s56, 0x2000
	s_nop 0
	global_load_lds_dwordx4 v94, s[54:55]
	s_add_u32 s54, s54, s6
	s_addc_u32 s55, s55, 0
	s_add_i32 s56, s57, s25
	s_mov_b32 m0, s56
	s_nop 0
	global_load_lds_dwordx4 v0, s[54:55]
	s_add_i32 m0, s56, 0x2000
	s_nop 0
	global_load_lds_dwordx4 v94, s[54:55]
	s_mov_b32 m0, s28
	s_nop 0
	global_load_lds_dwordx4 v0, s[30:31]
	s_mov_b32 m0, s29
	s_nop 0
	global_load_lds_dwordx4 v94, s[30:31]
	s_waitcnt vmcnt(8)
	s_waitcnt lgkmcnt(0)
	s_barrier
	s_setprio 1
	s_waitcnt lgkmcnt(0)
	v_mfma_f32_16x16x32_bf16 v[62:65], v[140:143], v[172:175], v[62:65]
	v_mfma_f32_16x16x32_bf16 v[58:61], v[148:151], v[172:175], v[58:61]
	v_mfma_f32_16x16x32_bf16 v[46:49], v[140:143], v[180:183], v[46:49]
	v_mfma_f32_16x16x32_bf16 v[42:45], v[148:151], v[180:183], v[42:45]
	v_mfma_f32_16x16x32_bf16 v[30:33], v[140:143], v[188:191], v[30:33]
	v_mfma_f32_16x16x32_bf16 v[26:29], v[148:151], v[188:191], v[26:29]
	v_mfma_f32_16x16x32_bf16 v[14:17], v[140:143], v[208:211], v[14:17]
	v_mfma_f32_16x16x32_bf16 v[10:13], v[148:151], v[208:211], v[10:13]
	v_mfma_f32_16x16x32_bf16 v[62:65], v[144:147], v[176:179], v[62:65]
	v_mfma_f32_16x16x32_bf16 v[58:61], v[152:155], v[176:179], v[58:61]
	v_mfma_f32_16x16x32_bf16 v[46:49], v[144:147], v[184:187], v[46:49]
	v_mfma_f32_16x16x32_bf16 v[42:45], v[152:155], v[184:187], v[42:45]
	v_mfma_f32_16x16x32_bf16 v[30:33], v[144:147], v[192:195], v[30:33]
	v_mfma_f32_16x16x32_bf16 v[26:29], v[152:155], v[192:195], v[26:29]
	v_mfma_f32_16x16x32_bf16 v[14:17], v[144:147], v[212:215], v[14:17]
	v_mfma_f32_16x16x32_bf16 v[10:13], v[152:155], v[212:215], v[10:13]
	s_setprio 0
	s_setprio 1
	v_mfma_f32_16x16x32_bf16 v[54:57], v[156:159], v[172:175], v[54:57]
	v_mfma_f32_16x16x32_bf16 v[50:53], v[164:167], v[172:175], v[50:53]
	v_mfma_f32_16x16x32_bf16 v[38:41], v[156:159], v[180:183], v[38:41]
	v_mfma_f32_16x16x32_bf16 v[34:37], v[164:167], v[180:183], v[34:37]
	v_mfma_f32_16x16x32_bf16 v[22:25], v[156:159], v[188:191], v[22:25]
	v_mfma_f32_16x16x32_bf16 v[18:21], v[164:167], v[188:191], v[18:21]
	v_mfma_f32_16x16x32_bf16 v[6:9], v[156:159], v[208:211], v[6:9]
	v_mfma_f32_16x16x32_bf16 v[2:5], v[164:167], v[208:211], v[2:5]
	v_mfma_f32_16x16x32_bf16 v[54:57], v[160:163], v[176:179], v[54:57]
	v_mfma_f32_16x16x32_bf16 v[50:53], v[168:171], v[176:179], v[50:53]
	v_mfma_f32_16x16x32_bf16 v[38:41], v[160:163], v[184:187], v[38:41]
	v_mfma_f32_16x16x32_bf16 v[34:37], v[168:171], v[184:187], v[34:37]
	v_mfma_f32_16x16x32_bf16 v[22:25], v[160:163], v[192:195], v[22:25]
	v_mfma_f32_16x16x32_bf16 v[18:21], v[168:171], v[192:195], v[18:21]
	v_mfma_f32_16x16x32_bf16 v[6:9], v[160:163], v[212:215], v[6:9]
	v_mfma_f32_16x16x32_bf16 v[2:5], v[168:171], v[212:215], v[2:5]
	s_setprio 0
	s_barrier
	s_add_i32 s56, 0, 0x18000
	s_add_i32 s57, 0, 0x1c000
	v_add_u32_e32 v152, s56, v232
	v_add_u32_e32 v168, s57, v232
	ds_read_b128 v[140:143], v152
	ds_read_b128 v[144:147], v152 offset:1024
	ds_read_b128 v[148:151], v152 offset:2048
	ds_read_b128 v[152:155], v152 offset:3072
	ds_read_b128 v[156:159], v168
	ds_read_b128 v[160:163], v168 offset:1024
	ds_read_b128 v[164:167], v168 offset:2048
	ds_read_b128 v[168:171], v168 offset:3072
	s_add_u32 s30, s30, s6
	s_addc_u32 s31, s31, 0
	s_mov_b32 m0, s33
	ds_read_b128 v[172:175], v236 offset:32768
	ds_read_b128 v[176:179], v236 offset:33792
	ds_read_b128 v[180:183], v236 offset:34816
	ds_read_b128 v[184:187], v236 offset:35840
	ds_read_b128 v[188:191], v236 offset:36864
	ds_read_b128 v[192:195], v236 offset:37888
	ds_read_b128 v[208:211], v236 offset:38912
	ds_read_b128 v[212:215], v236 offset:39936
	global_load_lds_dwordx4 v0, s[30:31]
	s_mov_b32 m0, s42
	s_nop 0
	global_load_lds_dwordx4 v94, s[30:31]
	s_waitcnt vmcnt(8)
	s_waitcnt lgkmcnt(0)
	s_barrier
	s_setprio 1
	s_waitcnt lgkmcnt(0)
	v_mfma_f32_16x16x32_bf16 v[130:133], v[140:143], v[172:175], v[130:133]
	v_mfma_f32_16x16x32_bf16 v[126:129], v[148:151], v[172:175], v[126:129]
	v_mfma_f32_16x16x32_bf16 v[114:117], v[140:143], v[180:183], v[114:117]
	v_mfma_f32_16x16x32_bf16 v[110:113], v[148:151], v[180:183], v[110:113]
	v_mfma_f32_16x16x32_bf16 v[98:101], v[140:143], v[188:191], v[98:101]
	v_mfma_f32_16x16x32_bf16 v[90:93], v[148:151], v[188:191], v[90:93]
	v_mfma_f32_16x16x32_bf16 v[78:81], v[140:143], v[208:211], v[78:81]
	v_mfma_f32_16x16x32_bf16 v[74:77], v[148:151], v[208:211], v[74:77]
	v_mfma_f32_16x16x32_bf16 v[130:133], v[144:147], v[176:179], v[130:133]
	v_mfma_f32_16x16x32_bf16 v[126:129], v[152:155], v[176:179], v[126:129]
	v_mfma_f32_16x16x32_bf16 v[114:117], v[144:147], v[184:187], v[114:117]
	v_mfma_f32_16x16x32_bf16 v[110:113], v[152:155], v[184:187], v[110:113]
	v_mfma_f32_16x16x32_bf16 v[98:101], v[144:147], v[192:195], v[98:101]
	v_mfma_f32_16x16x32_bf16 v[90:93], v[152:155], v[192:195], v[90:93]
	v_mfma_f32_16x16x32_bf16 v[78:81], v[144:147], v[212:215], v[78:81]
	v_mfma_f32_16x16x32_bf16 v[74:77], v[152:155], v[212:215], v[74:77]
	s_setprio 0
	s_setprio 1
	v_mfma_f32_16x16x32_bf16 v[122:125], v[156:159], v[172:175], v[122:125]
	v_mfma_f32_16x16x32_bf16 v[118:121], v[164:167], v[172:175], v[118:121]
	v_mfma_f32_16x16x32_bf16 v[106:109], v[156:159], v[180:183], v[106:109]
	v_mfma_f32_16x16x32_bf16 v[102:105], v[164:167], v[180:183], v[102:105]
	v_mfma_f32_16x16x32_bf16 v[86:89], v[156:159], v[188:191], v[86:89]
	v_mfma_f32_16x16x32_bf16 v[82:85], v[164:167], v[188:191], v[82:85]
	v_mfma_f32_16x16x32_bf16 v[70:73], v[156:159], v[208:211], v[70:73]
	v_mfma_f32_16x16x32_bf16 v[66:69], v[164:167], v[208:211], v[66:69]
	v_mfma_f32_16x16x32_bf16 v[122:125], v[160:163], v[176:179], v[122:125]
	v_mfma_f32_16x16x32_bf16 v[118:121], v[168:171], v[176:179], v[118:121]
	v_mfma_f32_16x16x32_bf16 v[106:109], v[160:163], v[184:187], v[106:109]
	v_mfma_f32_16x16x32_bf16 v[102:105], v[168:171], v[184:187], v[102:105]
	v_mfma_f32_16x16x32_bf16 v[86:89], v[160:163], v[192:195], v[86:89]
	v_mfma_f32_16x16x32_bf16 v[82:85], v[168:171], v[192:195], v[82:85]
	v_mfma_f32_16x16x32_bf16 v[70:73], v[160:163], v[212:215], v[70:73]
	v_mfma_f32_16x16x32_bf16 v[66:69], v[168:171], v[212:215], v[66:69]
	s_setprio 0
	s_barrier
	s_add_i32 s71, s56, s25
	s_sub_u32 s54, s54, s6
	s_subb_u32 s55, s55, 0
	s_add_u32 s54, s54, 0x80
	s_addc_u32 s55, s55, 0
	s_mov_b32 m0, s71
	ds_read_b128 v[172:175], v236 offset:49152
	ds_read_b128 v[176:179], v236 offset:50176
	ds_read_b128 v[180:183], v236 offset:51200
	ds_read_b128 v[184:187], v236 offset:52224
	ds_read_b128 v[188:191], v236 offset:53248
	ds_read_b128 v[192:195], v236 offset:54272
	ds_read_b128 v[208:211], v236 offset:55296
	ds_read_b128 v[212:215], v236 offset:56320
	global_load_lds_dwordx4 v0, s[54:55]
	s_add_i32 m0, s71, 0x2000
	s_nop 0
	global_load_lds_dwordx4 v94, s[54:55]
	s_add_i32 s71, s57, s25
	s_add_u32 s54, s54, s6
	s_addc_u32 s55, s55, 0
	s_mov_b32 m0, s71
	s_nop 0
	global_load_lds_dwordx4 v0, s[54:55]
	s_add_i32 m0, s71, 0x2000
	s_nop 0
	global_load_lds_dwordx4 v94, s[54:55]
	s_sub_u32 s30, s30, s6
	s_subb_u32 s31, s31, 0
	s_add_u32 s30, s30, 0x80
	s_addc_u32 s31, s31, 0
	s_mov_b32 m0, s43
	s_nop 0
	global_load_lds_dwordx4 v0, s[30:31]
	s_mov_b32 m0, s44
	s_nop 0
	global_load_lds_dwordx4 v94, s[30:31]
	s_waitcnt vmcnt(8)
	s_waitcnt lgkmcnt(0)
	s_barrier
	s_setprio 1
	s_waitcnt lgkmcnt(0)
	v_mfma_f32_16x16x32_bf16 v[62:65], v[140:143], v[172:175], v[62:65]
	v_mfma_f32_16x16x32_bf16 v[58:61], v[148:151], v[172:175], v[58:61]
	v_mfma_f32_16x16x32_bf16 v[46:49], v[140:143], v[180:183], v[46:49]
	v_mfma_f32_16x16x32_bf16 v[42:45], v[148:151], v[180:183], v[42:45]
	v_mfma_f32_16x16x32_bf16 v[30:33], v[140:143], v[188:191], v[30:33]
	v_mfma_f32_16x16x32_bf16 v[26:29], v[148:151], v[188:191], v[26:29]
	v_mfma_f32_16x16x32_bf16 v[14:17], v[140:143], v[208:211], v[14:17]
	v_mfma_f32_16x16x32_bf16 v[10:13], v[148:151], v[208:211], v[10:13]
	v_mfma_f32_16x16x32_bf16 v[62:65], v[144:147], v[176:179], v[62:65]
	v_mfma_f32_16x16x32_bf16 v[58:61], v[152:155], v[176:179], v[58:61]
	v_mfma_f32_16x16x32_bf16 v[46:49], v[144:147], v[184:187], v[46:49]
	v_mfma_f32_16x16x32_bf16 v[42:45], v[152:155], v[184:187], v[42:45]
	v_mfma_f32_16x16x32_bf16 v[30:33], v[144:147], v[192:195], v[30:33]
	v_mfma_f32_16x16x32_bf16 v[26:29], v[152:155], v[192:195], v[26:29]
	v_mfma_f32_16x16x32_bf16 v[14:17], v[144:147], v[212:215], v[14:17]
	v_mfma_f32_16x16x32_bf16 v[10:13], v[152:155], v[212:215], v[10:13]
	s_setprio 0
	s_setprio 1
	v_mfma_f32_16x16x32_bf16 v[54:57], v[156:159], v[172:175], v[54:57]
	v_mfma_f32_16x16x32_bf16 v[50:53], v[164:167], v[172:175], v[50:53]
	v_mfma_f32_16x16x32_bf16 v[38:41], v[156:159], v[180:183], v[38:41]
	v_mfma_f32_16x16x32_bf16 v[34:37], v[164:167], v[180:183], v[34:37]
	v_mfma_f32_16x16x32_bf16 v[22:25], v[156:159], v[188:191], v[22:25]
	v_mfma_f32_16x16x32_bf16 v[18:21], v[164:167], v[188:191], v[18:21]
	v_mfma_f32_16x16x32_bf16 v[6:9], v[156:159], v[208:211], v[6:9]
	v_mfma_f32_16x16x32_bf16 v[2:5], v[164:167], v[208:211], v[2:5]
	v_mfma_f32_16x16x32_bf16 v[54:57], v[160:163], v[176:179], v[54:57]
	v_mfma_f32_16x16x32_bf16 v[50:53], v[168:171], v[176:179], v[50:53]
	v_mfma_f32_16x16x32_bf16 v[38:41], v[160:163], v[184:187], v[38:41]
	v_mfma_f32_16x16x32_bf16 v[34:37], v[168:171], v[184:187], v[34:37]
	v_mfma_f32_16x16x32_bf16 v[22:25], v[160:163], v[192:195], v[22:25]
	v_mfma_f32_16x16x32_bf16 v[18:21], v[168:171], v[192:195], v[18:21]
	v_mfma_f32_16x16x32_bf16 v[6:9], v[160:163], v[212:215], v[6:9]
	v_mfma_f32_16x16x32_bf16 v[2:5], v[168:171], v[212:215], v[2:5]
	s_setprio 0
	s_barrier
	s_add_u32 s51, s51, 0x100
	s_addc_u32 s52, s52, 0
	s_add_u32 s22, s22, 0x100
	s_addc_u32 s23, s23, 0
	s_cmp_ge_u32 s53, s45
	s_mov_b32 s30, s53
	s_cbranch_scc0 .LBB0_528
	s_and_b64 vcc, exec, s[10:11]
	s_cbranch_vccz .LBB0_531
	s_barrier
